# v7 plus first two V reads of the PV step issued in the last score tile's tail
# baseline (speedup 1.0000x reference)
; __device__ __forceinline__ unsigned cvt_pk_bf16(float lo, float hi) { const bf16x2_cv v = __builtin_convertvector((f32x2_cv){lo, hi}, bf16x2_cv); return __builtin_bit_cast(unsigned, v); }
; #define LAS __attribute__((address_space(3)))
; __device__ __forceinline__ void retention_fused(const Params& p, LAS unsigned char* lds, int unit) {
;     ...
;         for (int a = 0; 2 * a <= wid; ++a) {
;             {
;                 f32x4 sc[2];
; #pragma unroll
;                 for (int t = 0; t < 2; ++t) { const int jt = 2 * a + t;
;                     sc[t] = (f32x4){0.f, 0.f, 0.f, 0.f};
;                     if (jt <= wid) {
; #pragma unroll
;                         for (int ks = 0; ks < 8; ++ks) { const bf16x8 kf = *(const LAS bf16x8*)(Ks + (jt * 16 + fr) * KS_STRIDE + ks * 64 + fq * 16);
;                             sc[t] = __builtin_amdgcn_mfma_f32_16x16x32_bf16(kf, qf[ks], sc[t], 0, 0, 0); }
;                         const float tf = __builtin_amdgcn_exp2f((float)(16 * (wid - jt)) * log2g);
; #pragma unroll
;                         for (int r = 0; r < 4; ++r) { const int dij = 16 * (wid - jt) + fr - fq * 4 - r;
;                             sc[t][r] = dij >= 0 ? sc[t][r] * (tf * __builtin_amdgcn_exp2f((float)(fr - fq * 4 - r) * log2g)) : 0.f; }
;                     } }
;                 bf16x8 pa; { const u32x4 w = (u32x4){cvt_pk_bf16(sc[0][0], sc[0][1]), cvt_pk_bf16(sc[0][2], sc[0][3]), cvt_pk_bf16(sc[1][0], sc[1][1]), cvt_pk_bf16(sc[1][2], sc[1][3])}; pa = __builtin_bit_cast(bf16x8, w); }
; #pragma unroll
;                 for (int nt = 0; nt < 4; ++nt) {
;                     LAS const unsigned char* a0 = Vs + (32 * a + fq * 4 + (fr >> 2)) * VS_STRIDE + (nt * 16 + 4 * (fr & 3)) * 2;
;                     const bf16x8 vf = tr_read2(a0, a0 + 16 * VS_STRIDE);
;                     o[nt] = __builtin_amdgcn_mfma_f32_16x16x32_bf16(pa, vf, o[nt], 0, 0, 0); }
.LBB0_1047:
	ds_read_b128 v[230:233], v224 offset:8576
	ds_read_b128 v[234:237], v224 offset:8640
	ds_read_b128 v[238:241], v224 offset:8704
	ds_read_b128 v[242:245], v224 offset:8768
	v_add_u32_e32 v246, -16, v225
	s_add_i32 s28, s27, -16
	s_waitcnt lgkmcnt(5)
	v_mfma_f32_16x16x32_bf16 v[226:229], v[248:251], v[82:85], 0
	s_waitcnt lgkmcnt(4)
	v_mfma_f32_16x16x32_bf16 v[226:229], v[252:255], v[86:89], v[226:229]
	s_waitcnt lgkmcnt(3)
	v_mfma_f32_16x16x32_bf16 v[226:229], v[230:233], v[90:93], v[226:229]
	ds_read_b128 v[230:233], v224 offset:8832
	s_waitcnt lgkmcnt(3)
	v_mfma_f32_16x16x32_bf16 v[226:229], v[234:237], v[94:97], v[226:229]
	ds_read_b128 v[234:237], v224 offset:8896
	s_waitcnt lgkmcnt(3)
	v_mfma_f32_16x16x32_bf16 v[224:227], v[238:241], v[98:101], v[226:229]
	v_sub_u32_e32 v238, v246, v130
	v_sub_u32_e32 v239, v246, v1
	v_cmp_lt_i32_e32 vcc, -1, v238
	s_waitcnt lgkmcnt(2)
	v_mfma_f32_16x16x32_bf16 v[224:227], v[242:245], v[102:105], v[224:227]
	v_cvt_f32_i32_e32 v228, s28
	v_sub_u32_e32 v240, v246, v152
	v_mul_f32_e32 v228, v153, v228
	s_waitcnt lgkmcnt(1)
	v_mfma_f32_16x16x32_bf16 v[224:227], v[230:233], v[106:109], v[224:227]
	v_exp_f32_e32 v228, v228
	v_sub_u32_e32 v232, v246, v115
	v_pk_mul_f32 v[230:231], v[150:151], v[228:229] op_sel_hi:[1,0]
	s_waitcnt lgkmcnt(0)
	v_mfma_f32_16x16x32_bf16 v[224:227], v[234:237], v[110:113], v[224:227]
	ds_read_b128 v[248:251], v163 offset:16896
	ds_read_b128 v[252:255], v163 offset:16960
	v_add_u32_e32 v246, 0x10800, v117
	v_add_u32_e32 v241, 0x11080, v117
	ds_read_b64_tr_b16 v[242:243], v246
	ds_read_b64_tr_b16 v[244:245], v241
	v_pk_mul_f32 v[228:229], v[154:155], v[228:229] op_sel_hi:[1,0]
	s_nop 0
	v_pk_mul_f32 v[224:225], v[230:231], v[224:225]
	v_pk_mul_f32 v[228:229], v[228:229], v[226:227]
	v_cndmask_b32_e32 v226, 0, v224, vcc
	v_cmp_lt_i32_e32 vcc, -1, v239
	s_nop 1
	v_cndmask_b32_e32 v224, 0, v225, vcc
	v_cmp_lt_i32_e32 vcc, -1, v240
	s_nop 1
	v_cndmask_b32_e32 v225, 0, v228, vcc
	v_cmp_lt_i32_e32 vcc, -1, v232
	s_nop 1
	v_cndmask_b32_e32 v227, 0, v229, vcc
.LBB0_1048:
	v_cvt_pk_bf16_f32 v228, v221, v179
	v_add_u32_e32 v179, 0, v117
	v_cvt_pk_bf16_f32 v230, v226, v224
	v_cvt_pk_bf16_f32 v229, v223, v222
	v_cvt_pk_bf16_f32 v231, v225, v227
	v_add_u32_e32 v221, 0x10820, v179
	v_add_u32_e32 v226, 0x110a0, v179
	ds_read_b64_tr_b16 v[232:233], v221
	ds_read_b64_tr_b16 v[234:235], v226
	s_waitcnt lgkmcnt(2)
	v_mfma_f32_16x16x32_bf16 v[62:65], v[228:231], v[242:245], v[62:65]
	v_add_u32_e32 v221, 0x10840, v179
	v_add_u32_e32 v224, 0x110c0, v179
	ds_read_b64_tr_b16 v[222:223], v221
	ds_read_b64_tr_b16 v[224:225], v224
	v_add_u32_e32 v221, 0x10860, v179
	s_waitcnt lgkmcnt(2)
	v_mfma_f32_16x16x32_bf16 v[58:61], v[228:231], v[232:235], v[58:61]
	v_add_u32_e32 v179, 0x110e0, v179
	ds_read_b64_tr_b16 v[232:233], v221
	ds_read_b64_tr_b16 v[234:235], v179
	s_sub_i32 s27, s27, 32
	s_waitcnt lgkmcnt(2)
	v_mfma_f32_16x16x32_bf16 v[54:57], v[228:231], v[222:225], v[54:57]
	s_add_i32 s26, s26, 2
	v_add_u32_e32 v163, 0x4200, v163
	s_cmp_eq_u32 s50, s26
	s_waitcnt lgkmcnt(0)
	v_mfma_f32_16x16x32_bf16 v[50:53], v[228:231], v[232:235], v[50:53]
	v_add_u32_e32 v117, 0x1100, v117
	s_cbranch_scc1 .LBB0_1051
.LBB0_1049:
	v_add_u32_e32 v224, 0, v163
	ds_read_b128 v[230:233], v224 offset:128
	ds_read_b128 v[234:237], v224 offset:192
	ds_read_b128 v[238:241], v224 offset:256
	ds_read_b128 v[242:245], v224 offset:320
	v_cvt_f32_i32_e32 v179, s27
	v_add_u32_e32 v225, s27, v114
	s_waitcnt lgkmcnt(5)
	v_mfma_f32_16x16x32_bf16 v[226:229], v[248:251], v[82:85], 0
	v_sub_u32_e32 v221, v225, v1
	v_mul_f32_e32 v179, v153, v179
	v_exp_f32_e32 v222, v179
	s_waitcnt lgkmcnt(4)
	v_mfma_f32_16x16x32_bf16 v[226:229], v[252:255], v[86:89], v[226:229]
	v_sub_u32_e32 v246, v225, v130
	v_cmp_lt_i32_e32 vcc, -1, v221
	s_waitcnt lgkmcnt(3)
	v_mfma_f32_16x16x32_bf16 v[226:229], v[230:233], v[90:93], v[226:229]
	ds_read_b128 v[230:233], v224 offset:384
	s_cmp_lt_u32 s26, s17
	s_waitcnt lgkmcnt(3)
	v_mfma_f32_16x16x32_bf16 v[226:229], v[234:237], v[94:97], v[226:229]
	ds_read_b128 v[234:237], v224 offset:448
	s_waitcnt lgkmcnt(3)
	v_mfma_f32_16x16x32_bf16 v[226:229], v[238:241], v[98:101], v[226:229]
	s_waitcnt lgkmcnt(2)
	v_mfma_f32_16x16x32_bf16 v[226:229], v[242:245], v[102:105], v[226:229]
	v_sub_u32_e32 v238, v225, v115
	s_waitcnt lgkmcnt(1)
	v_mfma_f32_16x16x32_bf16 v[226:229], v[230:233], v[106:109], v[226:229]
	v_mul_f32_e64 v230, v150, v222
	v_mul_f32_e64 v231, v151, v222
	v_pk_mul_f32 v[222:223], v[154:155], v[222:223] op_sel_hi:[1,0]
	v_sub_u32_e32 v232, v225, v152
	s_waitcnt lgkmcnt(0)
	v_mfma_f32_16x16x32_bf16 v[226:229], v[234:237], v[110:113], v[226:229]
	ds_read_b128 v[248:251], v224 offset:8448
	ds_read_b128 v[252:255], v224 offset:8512
	s_nop 5
	v_pk_mul_f32 v[226:227], v[230:231], v[226:227]
	v_pk_mul_f32 v[228:229], v[222:223], v[228:229]
	v_cndmask_b32_e32 v179, 0, v227, vcc
	v_cmp_lt_i32_e32 vcc, -1, v246
	s_nop 1
	v_cndmask_b32_e32 v221, 0, v226, vcc
	v_cmp_lt_i32_e32 vcc, -1, v238
	v_mov_b32_e32 v226, 0
	s_nop 0
	v_cndmask_b32_e32 v222, 0, v229, vcc
	v_cmp_lt_i32_e32 vcc, -1, v232
	s_nop 1
	v_cndmask_b32_e32 v223, 0, v228, vcc
	s_cbranch_scc1 .LBB0_1047
	v_mov_b32_e32 v224, 0
	v_mov_b32_e32 v225, 0
	v_mov_b32_e32 v227, 0
	v_add_u32_e32 v246, 0x10800, v117
	v_add_u32_e32 v241, 0x11080, v117
	ds_read_b64_tr_b16 v[242:243], v246
	ds_read_b64_tr_b16 v[244:245], v241
	s_branch .LBB0_1048
